# flips deleted + one static s_setprio 1 for waves 0-3 at kernel entry
# speedup vs baseline: 1.0028x; 1.0028x over previous
; #define LAS __attribute__((address_space(3)))
; __device__ __forceinline__ unsigned xb_add(unsigned* p, unsigned v) { return __hip_atomic_fetch_add(p, v, __ATOMIC_RELAXED, __HIP_MEMORY_SCOPE_AGENT); }
; __device__ __forceinline__ unsigned xb_xcc_id() { return (unsigned)__builtin_amdgcn_s_getreg((3 << 11) | 20) & 0xFu; }
; #define LOADP(Pl) Params Pl; { CParams q_ = pk; asm volatile("" : "+s"(q_)); Pl = *q_; }
; __device__ __forceinline__ XcdBarrier xcd_barrier_post(unsigned* bar, volatile LAS unsigned* st) {
;     XcdBarrier b; b.bar = bar; b.x = xb_xcc_id(); b.st = st;
;     if (threadIdx.x == 0) (void)xb_add(&bar[XB_XCNT(b.x)], 1u);
;     return b;
; __global__ void __launch_bounds__(512) fwd_megakernel(Params Parg) {
;     ...
;     if (threadIdx.x == 0) { xst[0] = 0u; xst[1] = 0u; }
;     __syncthreads();
;     XcdBarrier xb; { LOADP(P) xb = xcd_barrier_post((unsigned*)(P.ws + OFF_BAR), xst); }
.LBB0_2:
	s_or_b64 exec, exec, s[8:9]
	v_readfirstlane_b32 vcc_lo, v186
	s_cmpk_gt_u32 vcc_lo, 0xff
	s_cbranch_scc1 .Lprio_static_done
	s_setprio 1
